# IN rotary-key 128x128 tiles: drop global loads + LDS writes of the 96 zero-padding weight rows (B sub-blocks 1-3, results never stored); vmcnt recomputed
# speedup vs baseline: 1.0142x; 1.0053x over previous
.LBB0_556:
	v_lshrrev_b32_e32 v248, 2, v200
	v_and_b32_e32 v248, 8, v248
	v_mov_b32_e32 v249, 0
	v_and_b32_e32 v52, 0xff, v200
	s_movk_i32 s2, 0x4000
	v_ashrrev_i32_e32 v48, 3, v52
	v_add3_u32 v2, v51, v48, s2
	v_ashrrev_i32_e32 v3, 31, v2
	v_lshlrev_b64 v[2:3], 11, v[2:3]
	v_lshlrev_b32_e32 v0, 4, v52
	v_and_b32_e32 v0, 0x70, v0
	v_lshl_add_u64 v[2:3], s[82:83], 0, v[2:3]
	v_lshl_add_u64 v[34:35], v[2:3], 0, v[0:1]
	s_mov_b32 s0, 0x10000
	v_ashrrev_i32_e32 v49, 31, v48
	v_add_co_u32_e32 v36, vcc, s0, v34
	v_lshlrev_b64 v[4:5], 11, v[48:49]
	s_nop 0
	v_addc_co_u32_e32 v37, vcc, 0, v35, vcc
	v_lshl_add_u64 v[4:5], s[84:85], 0, v[4:5]
	v_add_co_u32_e32 v38, vcc, s7, v34
	v_lshl_add_u64 v[56:57], v[4:5], 0, v[0:1]
	s_nop 0
	v_addc_co_u32_e32 v39, vcc, 0, v35, vcc
	s_mov_b32 s0, 0x380000
	v_add_co_u32_e32 v14, vcc, s0, v56
	s_mov_b32 s0, 0x390000
	s_nop 0
	v_addc_co_u32_e32 v15, vcc, 0, v57, vcc
	v_add_co_u32_e32 v40, vcc, s0, v56
	s_mov_b32 s0, 0x3a0000
	s_nop 0
	v_addc_co_u32_e32 v41, vcc, 0, v57, vcc
	global_load_dwordx4 v[2:5], v[34:35], off
	global_load_dwordx4 v[6:9], v[36:37], off
	global_load_dwordx4 v[10:13], v[38:39], off
	s_nop 0
	global_load_dwordx4 v[14:17], v[14:15], off
	s_nop 0
	v_add_co_u32_e32 v42, vcc, s0, v56
	s_mov_b32 s0, 0x3b0000
	s_nop 0
	v_addc_co_u32_e32 v43, vcc, 0, v57, vcc
	v_add_co_u32_e32 v44, vcc, s0, v56
	s_nop 0
	v_addc_co_u32_e32 v45, vcc, 0, v57, vcc
	v_add_co_u32_e32 v46, vcc, s54, v34
	v_lshrrev_b32_e32 v49, 1, v52
	s_nop 0
	v_addc_co_u32_e32 v47, vcc, 0, v35, vcc
	global_load_dwordx4 v[30:33], v[46:47], off
	v_and_b32_e32 v54, 0x1f, v52
	v_mul_lo_u32 v48, v48, s4
	v_and_b32_e32 v122, 16, v49
	v_mul_u32_u24_e32 v49, 0x90, v54
	s_mov_b64 s[0:1], 0x380000
	v_add3_u32 v54, v48, v0, v232
	v_add3_u32 v0, v49, v122, v232
	v_lshl_add_u64 v[48:49], v[56:57], 0, s[0:1]
	global_load_dwordx4 v[58:61], v[34:35], off offset:128
	global_load_dwordx4 v[86:89], v[48:49], off offset:128
	global_load_dwordx4 v[90:93], v[48:49], off offset:256
	global_load_dwordx4 v[94:97], v[36:37], off offset:128
	global_load_dwordx4 v[98:101], v[38:39], off offset:128
	global_load_dwordx4 v[102:105], v[46:47], off offset:128
	global_load_dwordx4 v[106:109], v[46:47], off offset:256
	global_load_dwordx4 v[110:113], v[38:39], off offset:256
	global_load_dwordx4 v[114:117], v[36:37], off offset:256
	global_load_dwordx4 v[118:121], v[34:35], off offset:256
	v_and_b32_e32 v53, 31, v52
	v_ashrrev_i32_e32 v55, 1, v52
	s_movk_i32 s0, 0xffc0
	v_and_or_b32 v55, v55, s0, v53
	v_add_u32_e32 v57, 0x9000, v54
	s_waitcnt vmcnt(14)
	ds_write_b128 v54, v[2:5]
	s_waitcnt vmcnt(11)
	ds_write_b128 v54, v[14:17] offset:18432
	s_waitcnt vmcnt(11)
	s_waitcnt vmcnt(11)
	s_waitcnt vmcnt(11)
	ds_write_b128 v54, v[6:9] offset:4608
	ds_write_b128 v54, v[10:13] offset:9216
	s_waitcnt vmcnt(10)
	ds_write_b128 v54, v[30:33] offset:13824
	s_waitcnt lgkmcnt(0)
	s_barrier
	ds_read_b128 v[2:5], v0 offset:18432
	v_mul_lo_u32 v6, v55, s4
	v_add3_u32 v56, v6, v122, v232
	ds_read_b128 v[6:9], v56
	ds_read_b128 v[122:125], v56 offset:32
	ds_read_b128 v[126:129], v0 offset:18464
	s_waitcnt lgkmcnt(2)
	v_mfma_f32_32x32x16_bf16 v[18:33], v[2:5], v[6:9], 0
	ds_read_b128 v[6:9], v56 offset:4608
	ds_read_b128 v[130:133], v56 offset:4640
	s_waitcnt lgkmcnt(1)
	v_mfma_f32_32x32x16_bf16 v[2:17], v[2:5], v[6:9], 0
	v_mfma_f32_32x32x16_bf16 v[18:33], v[126:129], v[122:125], v[18:33]
	s_waitcnt lgkmcnt(0)
	v_mfma_f32_32x32x16_bf16 v[2:17], v[126:129], v[130:133], v[2:17]
	ds_read_b128 v[122:125], v0 offset:18496
	ds_read_b128 v[126:129], v56 offset:64
	ds_read_b128 v[130:133], v56 offset:96
	ds_read_b128 v[134:137], v0 offset:18528
	s_waitcnt lgkmcnt(2)
	v_mfma_f32_32x32x16_bf16 v[18:33], v[122:125], v[126:129], v[18:33]
	ds_read_b128 v[126:129], v56 offset:4672
	ds_read_b128 v[138:141], v56 offset:4704
	s_waitcnt lgkmcnt(1)
	v_mfma_f32_32x32x16_bf16 v[2:17], v[122:125], v[126:129], v[2:17]
	global_load_dwordx4 v[122:125], v[36:37], off offset:384
	global_load_dwordx4 v[126:129], v[38:39], off offset:384
	global_load_dwordx4 v[142:145], v[34:35], off offset:384
	global_load_dwordx4 v[146:149], v[48:49], off offset:384
	v_mfma_f32_32x32x16_bf16 v[18:33], v[134:137], v[130:133], v[18:33]
	global_load_dwordx4 v[130:133], v[46:47], off offset:384
	s_waitcnt vmcnt(14)
	ds_write_b128 v54, v[58:61] offset:36864
	s_waitcnt vmcnt(11)
	ds_write_b128 v54, v[94:97] offset:41472
	s_waitcnt vmcnt(10)
	ds_write_b128 v54, v[98:101] offset:46080
	s_waitcnt vmcnt(9)
	ds_write_b128 v54, v[102:105] offset:50688
	ds_write_b128 v54, v[86:89] offset:55296
	s_waitcnt lgkmcnt(0)
	s_barrier
	ds_read_b128 v[58:61], v0 offset:55296
	ds_read_b128 v[62:65], v56 offset:36864
	ds_read_b128 v[66:69], v56 offset:36896
	ds_read_b128 v[78:81], v0 offset:55328
	v_mfma_f32_32x32x16_bf16 v[2:17], v[134:137], v[138:141], v[2:17]
	s_waitcnt lgkmcnt(2)
	v_mfma_f32_32x32x16_bf16 v[18:33], v[58:61], v[62:65], v[18:33]
	ds_read_b128 v[62:65], v56 offset:41472
	ds_read_b128 v[86:89], v56 offset:41504
	s_waitcnt lgkmcnt(1)
	v_mfma_f32_32x32x16_bf16 v[2:17], v[58:61], v[62:65], v[2:17]
	v_mfma_f32_32x32x16_bf16 v[18:33], v[78:81], v[66:69], v[18:33]
	s_waitcnt lgkmcnt(0)
	v_mfma_f32_32x32x16_bf16 v[2:17], v[78:81], v[86:89], v[2:17]
	ds_read_b128 v[58:61], v0 offset:55360
	ds_read_b128 v[62:65], v56 offset:36928
	ds_read_b128 v[66:69], v56 offset:36960
	ds_read_b128 v[78:81], v0 offset:55392
	s_waitcnt lgkmcnt(2)
	v_mfma_f32_32x32x16_bf16 v[18:33], v[58:61], v[62:65], v[18:33]
	ds_read_b128 v[62:65], v56 offset:41536
	ds_read_b128 v[86:89], v56 offset:41568
	s_waitcnt lgkmcnt(1)
	v_mfma_f32_32x32x16_bf16 v[2:17], v[58:61], v[62:65], v[2:17]
	v_add_u32_e32 v58, 0x10e00, v54
	v_mfma_f32_32x32x16_bf16 v[18:33], v[78:81], v[66:69], v[18:33]
	global_load_dwordx4 v[60:63], v[36:37], off offset:512
	global_load_dwordx4 v[64:67], v[38:39], off offset:512
	global_load_dwordx4 v[94:97], v[34:35], off offset:512
	global_load_dwordx4 v[98:101], v[48:49], off offset:512
	global_load_dwordx4 v[102:105], v[46:47], off offset:512
	s_waitcnt vmcnt(10)
	ds_write_b128 v54, v[118:121]
	ds_write_b128 v54, v[114:117] offset:4608
	ds_write_b128 v54, v[110:113] offset:9216
	ds_write_b128 v54, v[106:109] offset:13824
	ds_write_b128 v54, v[90:93] offset:18432
	s_waitcnt lgkmcnt(0)
	s_barrier
	v_mfma_f32_32x32x16_bf16 v[2:17], v[78:81], v[86:89], v[2:17]
	ds_read_b128 v[68:71], v0 offset:18432
	ds_read_b128 v[72:75], v56
	ds_read_b128 v[76:79], v56 offset:32
	ds_read_b128 v[80:83], v0 offset:18464
	s_waitcnt lgkmcnt(2)
	v_mfma_f32_32x32x16_bf16 v[18:33], v[68:71], v[72:75], v[18:33]
	ds_read_b128 v[72:75], v56 offset:4608
	ds_read_b128 v[84:87], v56 offset:4640
	s_waitcnt lgkmcnt(1)
	v_mfma_f32_32x32x16_bf16 v[2:17], v[68:71], v[72:75], v[2:17]
	v_mfma_f32_32x32x16_bf16 v[18:33], v[80:83], v[76:79], v[18:33]
	s_waitcnt lgkmcnt(0)
	v_mfma_f32_32x32x16_bf16 v[2:17], v[80:83], v[84:87], v[2:17]
	ds_read_b128 v[68:71], v0 offset:18496
	ds_read_b128 v[72:75], v56 offset:64
	ds_read_b128 v[76:79], v56 offset:96
	ds_read_b128 v[80:83], v0 offset:18528
	s_waitcnt lgkmcnt(2)
	v_mfma_f32_32x32x16_bf16 v[18:33], v[68:71], v[72:75], v[18:33]
	ds_read_b128 v[72:75], v56 offset:4672
	ds_read_b128 v[84:87], v56 offset:4704
	s_waitcnt lgkmcnt(1)
	v_mfma_f32_32x32x16_bf16 v[2:17], v[68:71], v[72:75], v[2:17]
	v_mfma_f32_32x32x16_bf16 v[18:33], v[80:83], v[76:79], v[18:33]
	global_load_dwordx4 v[68:71], v[36:37], off offset:640
	global_load_dwordx4 v[72:75], v[38:39], off offset:640
	global_load_dwordx4 v[76:79], v[34:35], off offset:640
	global_load_dwordx4 v[88:91], v[48:49], off offset:640
	global_load_dwordx4 v[106:109], v[46:47], off offset:640
	s_waitcnt vmcnt(12)
	ds_write_b128 v54, v[142:145] offset:36864
	ds_write_b128 v54, v[122:125] offset:41472
	ds_write_b128 v54, v[126:129] offset:46080
	s_waitcnt vmcnt(10)
	ds_write_b128 v54, v[130:133] offset:50688
	ds_write_b128 v54, v[146:149] offset:55296
	s_waitcnt vmcnt(10)
	s_waitcnt vmcnt(10)
	s_waitcnt vmcnt(10)
	s_waitcnt lgkmcnt(0)
	s_barrier
	v_mfma_f32_32x32x16_bf16 v[2:17], v[80:83], v[84:87], v[2:17]
	ds_read_b128 v[80:83], v0 offset:55296
	ds_read_b128 v[84:87], v56 offset:36864
	ds_read_b128 v[122:125], v56 offset:36896
	ds_read_b128 v[126:129], v0 offset:55328
	s_waitcnt lgkmcnt(2)
	v_mfma_f32_32x32x16_bf16 v[18:33], v[80:83], v[84:87], v[18:33]
	ds_read_b128 v[84:87], v56 offset:41472
	ds_read_b128 v[130:133], v56 offset:41504
	s_waitcnt lgkmcnt(1)
	v_mfma_f32_32x32x16_bf16 v[2:17], v[80:83], v[84:87], v[2:17]
	v_mfma_f32_32x32x16_bf16 v[18:33], v[126:129], v[122:125], v[18:33]
	s_waitcnt lgkmcnt(0)
	v_mfma_f32_32x32x16_bf16 v[2:17], v[126:129], v[130:133], v[2:17]
	ds_read_b128 v[80:83], v0 offset:55360
	ds_read_b128 v[84:87], v56 offset:36928
	ds_read_b128 v[122:125], v56 offset:36960
	ds_read_b128 v[126:129], v0 offset:55392
	s_waitcnt lgkmcnt(2)
	v_mfma_f32_32x32x16_bf16 v[18:33], v[80:83], v[84:87], v[18:33]
	ds_read_b128 v[84:87], v56 offset:41536
	ds_read_b128 v[130:133], v56 offset:41568
	s_waitcnt lgkmcnt(1)
	v_mfma_f32_32x32x16_bf16 v[2:17], v[80:83], v[84:87], v[2:17]
	v_mfma_f32_32x32x16_bf16 v[18:33], v[126:129], v[122:125], v[18:33]
	global_load_dwordx4 v[80:83], v[36:37], off offset:768
	global_load_dwordx4 v[84:87], v[38:39], off offset:768
	global_load_dwordx4 v[122:125], v[34:35], off offset:768
	global_load_dwordx4 v[142:145], v[48:49], off offset:768
	global_load_dwordx4 v[146:149], v[46:47], off offset:768
	s_waitcnt vmcnt(12)
	ds_write_b128 v54, v[94:97]
	ds_write_b128 v54, v[60:63] offset:4608
	ds_write_b128 v54, v[64:67] offset:9216
	s_waitcnt vmcnt(10)
	ds_write_b128 v54, v[102:105] offset:13824
	ds_write_b128 v54, v[98:101] offset:18432
	s_waitcnt vmcnt(10)
	s_waitcnt vmcnt(10)
	s_waitcnt vmcnt(10)
	s_waitcnt lgkmcnt(0)
	s_barrier
	ds_read_b128 v[60:63], v0 offset:18432
	ds_read_b128 v[64:67], v56
	ds_read_b128 v[92:95], v56 offset:32
	ds_read_b128 v[96:99], v0 offset:18464
	v_mfma_f32_32x32x16_bf16 v[2:17], v[126:129], v[130:133], v[2:17]
	s_waitcnt lgkmcnt(2)
	v_mfma_f32_32x32x16_bf16 v[18:33], v[60:63], v[64:67], v[18:33]
	ds_read_b128 v[64:67], v56 offset:4608
	ds_read_b128 v[100:103], v56 offset:4640
	s_waitcnt lgkmcnt(1)
	v_mfma_f32_32x32x16_bf16 v[2:17], v[60:63], v[64:67], v[2:17]
	v_mfma_f32_32x32x16_bf16 v[18:33], v[96:99], v[92:95], v[18:33]
	s_waitcnt lgkmcnt(0)
	v_mfma_f32_32x32x16_bf16 v[2:17], v[96:99], v[100:103], v[2:17]
	ds_read_b128 v[60:63], v0 offset:18496
	ds_read_b128 v[64:67], v56 offset:64
	ds_read_b128 v[92:95], v56 offset:96
	ds_read_b128 v[96:99], v0 offset:18528
	s_waitcnt lgkmcnt(2)
	v_mfma_f32_32x32x16_bf16 v[18:33], v[60:63], v[64:67], v[18:33]
	ds_read_b128 v[64:67], v56 offset:4672
	ds_read_b128 v[100:103], v56 offset:4704
	s_waitcnt lgkmcnt(1)
	v_mfma_f32_32x32x16_bf16 v[2:17], v[60:63], v[64:67], v[2:17]
	v_mfma_f32_32x32x16_bf16 v[18:33], v[96:99], v[92:95], v[18:33]
	global_load_dwordx4 v[60:63], v[36:37], off offset:896
	global_load_dwordx4 v[64:67], v[38:39], off offset:896
	global_load_dwordx4 v[92:95], v[34:35], off offset:896
	global_load_dwordx4 v[126:129], v[48:49], off offset:896
	global_load_dwordx4 v[130:133], v[46:47], off offset:896
	s_waitcnt vmcnt(12)
	ds_write_b128 v54, v[76:79] offset:36864
	ds_write_b128 v54, v[68:71] offset:41472
	ds_write_b128 v54, v[72:75] offset:46080
	s_waitcnt vmcnt(10)
	ds_write_b128 v54, v[106:109] offset:50688
	ds_write_b128 v54, v[88:91] offset:55296
	s_waitcnt vmcnt(10)
	s_waitcnt vmcnt(10)
	s_waitcnt vmcnt(10)
	s_waitcnt lgkmcnt(0)
	s_barrier
	ds_read_b128 v[68:71], v0 offset:55296
	ds_read_b128 v[72:75], v56 offset:36864
	ds_read_b128 v[76:79], v56 offset:36896
	ds_read_b128 v[88:91], v0 offset:55328
	v_mfma_f32_32x32x16_bf16 v[2:17], v[96:99], v[100:103], v[2:17]
	s_waitcnt lgkmcnt(2)
	v_mfma_f32_32x32x16_bf16 v[18:33], v[68:71], v[72:75], v[18:33]
	ds_read_b128 v[72:75], v56 offset:41472
	ds_read_b128 v[96:99], v56 offset:41504
	s_waitcnt lgkmcnt(1)
	v_mfma_f32_32x32x16_bf16 v[2:17], v[68:71], v[72:75], v[2:17]
	v_mfma_f32_32x32x16_bf16 v[18:33], v[88:91], v[76:79], v[18:33]
	s_waitcnt lgkmcnt(0)
	v_mfma_f32_32x32x16_bf16 v[2:17], v[88:91], v[96:99], v[2:17]
	ds_read_b128 v[68:71], v0 offset:55360
	ds_read_b128 v[72:75], v56 offset:36928
	ds_read_b128 v[76:79], v56 offset:36960
	ds_read_b128 v[88:91], v0 offset:55392
	s_waitcnt lgkmcnt(2)
	v_mfma_f32_32x32x16_bf16 v[18:33], v[68:71], v[72:75], v[18:33]
	ds_read_b128 v[72:75], v56 offset:41536
	ds_read_b128 v[96:99], v56 offset:41568
	s_waitcnt lgkmcnt(1)
	v_mfma_f32_32x32x16_bf16 v[2:17], v[68:71], v[72:75], v[2:17]
	v_mfma_f32_32x32x16_bf16 v[18:33], v[88:91], v[76:79], v[18:33]
	global_load_dwordx4 v[68:71], v[36:37], off offset:1024
	global_load_dwordx4 v[72:75], v[38:39], off offset:1024
	global_load_dwordx4 v[76:79], v[34:35], off offset:1024
	global_load_dwordx4 v[100:103], v[48:49], off offset:1024
	global_load_dwordx4 v[104:107], v[46:47], off offset:1024
	s_waitcnt vmcnt(12)
	ds_write_b128 v54, v[122:125]
	ds_write_b128 v54, v[80:83] offset:4608
	ds_write_b128 v54, v[84:87] offset:9216
	s_waitcnt vmcnt(10)
	ds_write_b128 v54, v[146:149] offset:13824
	ds_write_b128 v54, v[142:145] offset:18432
	s_waitcnt vmcnt(10)
	s_waitcnt vmcnt(10)
	s_waitcnt vmcnt(10)
	s_waitcnt lgkmcnt(0)
	s_barrier
	v_mfma_f32_32x32x16_bf16 v[2:17], v[88:91], v[96:99], v[2:17]
	ds_read_b128 v[80:83], v0 offset:18432
	ds_read_b128 v[84:87], v56
	ds_read_b128 v[88:91], v56 offset:32
	ds_read_b128 v[96:99], v0 offset:18464
	s_waitcnt lgkmcnt(2)
	v_mfma_f32_32x32x16_bf16 v[18:33], v[80:83], v[84:87], v[18:33]
	ds_read_b128 v[84:87], v56 offset:4608
	ds_read_b128 v[120:123], v56 offset:4640
	s_waitcnt lgkmcnt(1)
	v_mfma_f32_32x32x16_bf16 v[2:17], v[80:83], v[84:87], v[2:17]
	v_mfma_f32_32x32x16_bf16 v[18:33], v[96:99], v[88:91], v[18:33]
	s_waitcnt lgkmcnt(0)
	v_mfma_f32_32x32x16_bf16 v[2:17], v[96:99], v[120:123], v[2:17]
	ds_read_b128 v[80:83], v0 offset:18496
	ds_read_b128 v[84:87], v56 offset:64
	ds_read_b128 v[88:91], v56 offset:96
	ds_read_b128 v[96:99], v0 offset:18528
	s_waitcnt lgkmcnt(2)
	v_mfma_f32_32x32x16_bf16 v[18:33], v[80:83], v[84:87], v[18:33]
	ds_read_b128 v[84:87], v56 offset:4672
	ds_read_b128 v[120:123], v56 offset:4704
	s_waitcnt lgkmcnt(1)
	v_mfma_f32_32x32x16_bf16 v[2:17], v[80:83], v[84:87], v[2:17]
	v_mfma_f32_32x32x16_bf16 v[18:33], v[96:99], v[88:91], v[18:33]
	global_load_dwordx4 v[80:83], v[36:37], off offset:1152
	global_load_dwordx4 v[84:87], v[38:39], off offset:1152
	global_load_dwordx4 v[88:91], v[34:35], off offset:1152
	global_load_dwordx4 v[142:145], v[48:49], off offset:1152
	global_load_dwordx4 v[146:149], v[46:47], off offset:1152
	s_waitcnt vmcnt(12)
	ds_write_b128 v54, v[92:95] offset:36864
	ds_write_b128 v54, v[60:63] offset:41472
	ds_write_b128 v54, v[64:67] offset:46080
	s_waitcnt vmcnt(10)
	ds_write_b128 v54, v[130:133] offset:50688
	ds_write_b128 v54, v[126:129] offset:55296
	s_waitcnt vmcnt(10)
	s_waitcnt vmcnt(10)
	s_waitcnt vmcnt(10)
	s_waitcnt lgkmcnt(0)
	s_barrier
	v_mfma_f32_32x32x16_bf16 v[2:17], v[96:99], v[120:123], v[2:17]
	ds_read_b128 v[60:63], v0 offset:55296
	ds_read_b128 v[64:67], v56 offset:36864
	ds_read_b128 v[92:95], v56 offset:36896
	ds_read_b128 v[96:99], v0 offset:55328
	s_waitcnt lgkmcnt(2)
	v_mfma_f32_32x32x16_bf16 v[18:33], v[60:63], v[64:67], v[18:33]
	ds_read_b128 v[64:67], v56 offset:41472
	ds_read_b128 v[120:123], v56 offset:41504
	s_waitcnt lgkmcnt(1)
	v_mfma_f32_32x32x16_bf16 v[2:17], v[60:63], v[64:67], v[2:17]
	v_mfma_f32_32x32x16_bf16 v[18:33], v[96:99], v[92:95], v[18:33]
	s_waitcnt lgkmcnt(0)
	v_mfma_f32_32x32x16_bf16 v[2:17], v[96:99], v[120:123], v[2:17]
	ds_read_b128 v[60:63], v0 offset:55360
	ds_read_b128 v[64:67], v56 offset:36928
	ds_read_b128 v[92:95], v56 offset:36960
	ds_read_b128 v[96:99], v0 offset:55392
	s_waitcnt lgkmcnt(2)
	v_mfma_f32_32x32x16_bf16 v[18:33], v[60:63], v[64:67], v[18:33]
	ds_read_b128 v[64:67], v56 offset:41536
	ds_read_b128 v[120:123], v56 offset:41568
	s_waitcnt lgkmcnt(1)
	v_mfma_f32_32x32x16_bf16 v[2:17], v[60:63], v[64:67], v[2:17]
	v_mfma_f32_32x32x16_bf16 v[18:33], v[96:99], v[92:95], v[18:33]
	global_load_dwordx4 v[60:63], v[36:37], off offset:1280
	global_load_dwordx4 v[64:67], v[38:39], off offset:1280
	global_load_dwordx4 v[92:95], v[34:35], off offset:1280
	global_load_dwordx4 v[124:127], v[48:49], off offset:1280
	global_load_dwordx4 v[128:131], v[46:47], off offset:1280
	s_waitcnt vmcnt(12)
	ds_write_b128 v54, v[76:79]
	ds_write_b128 v54, v[68:71] offset:4608
	ds_write_b128 v54, v[72:75] offset:9216
	s_waitcnt vmcnt(10)
	ds_write_b128 v54, v[104:107] offset:13824
	ds_write_b128 v54, v[100:103] offset:18432
	s_waitcnt vmcnt(10)
	s_waitcnt vmcnt(10)
	s_waitcnt vmcnt(10)
	s_waitcnt lgkmcnt(0)
	s_barrier
	v_mfma_f32_32x32x16_bf16 v[2:17], v[96:99], v[120:123], v[2:17]
	ds_read_b128 v[68:71], v0 offset:18432
	ds_read_b128 v[72:75], v56
	ds_read_b128 v[76:79], v56 offset:32
	ds_read_b128 v[96:99], v0 offset:18464
	s_waitcnt lgkmcnt(2)
	v_mfma_f32_32x32x16_bf16 v[18:33], v[68:71], v[72:75], v[18:33]
	ds_read_b128 v[72:75], v56 offset:4608
	ds_read_b128 v[100:103], v56 offset:4640
	s_waitcnt lgkmcnt(1)
	v_mfma_f32_32x32x16_bf16 v[2:17], v[68:71], v[72:75], v[2:17]
	v_mfma_f32_32x32x16_bf16 v[18:33], v[96:99], v[76:79], v[18:33]
	s_waitcnt lgkmcnt(0)
	v_mfma_f32_32x32x16_bf16 v[2:17], v[96:99], v[100:103], v[2:17]
	ds_read_b128 v[68:71], v0 offset:18496
	ds_read_b128 v[72:75], v56 offset:64
	ds_read_b128 v[76:79], v56 offset:96
	ds_read_b128 v[96:99], v0 offset:18528
	s_waitcnt lgkmcnt(2)
	v_mfma_f32_32x32x16_bf16 v[18:33], v[68:71], v[72:75], v[18:33]
	ds_read_b128 v[72:75], v56 offset:4672
	ds_read_b128 v[100:103], v56 offset:4704
	s_waitcnt lgkmcnt(1)
	v_mfma_f32_32x32x16_bf16 v[2:17], v[68:71], v[72:75], v[2:17]
	v_mfma_f32_32x32x16_bf16 v[18:33], v[96:99], v[76:79], v[18:33]
	global_load_dwordx4 v[68:71], v[36:37], off offset:1408
	global_load_dwordx4 v[72:75], v[38:39], off offset:1408
	global_load_dwordx4 v[76:79], v[34:35], off offset:1408
	global_load_dwordx4 v[104:107], v[48:49], off offset:1408
	global_load_dwordx4 v[108:111], v[46:47], off offset:1408
	s_waitcnt vmcnt(12)
	ds_write_b128 v54, v[88:91] offset:36864
	ds_write_b128 v54, v[80:83] offset:41472
	ds_write_b128 v54, v[84:87] offset:46080
	s_waitcnt vmcnt(10)
	ds_write_b128 v54, v[146:149] offset:50688
	ds_write_b128 v54, v[142:145] offset:55296
	s_waitcnt vmcnt(10)
	s_waitcnt vmcnt(10)
	s_waitcnt vmcnt(10)
	s_waitcnt lgkmcnt(0)
	s_barrier
	v_mfma_f32_32x32x16_bf16 v[2:17], v[96:99], v[100:103], v[2:17]
	ds_read_b128 v[80:83], v0 offset:55296
	ds_read_b128 v[84:87], v56 offset:36864
	ds_read_b128 v[88:91], v56 offset:36896
	ds_read_b128 v[96:99], v0 offset:55328
	s_waitcnt lgkmcnt(2)
	v_mfma_f32_32x32x16_bf16 v[18:33], v[80:83], v[84:87], v[18:33]
	ds_read_b128 v[84:87], v56 offset:41472
	ds_read_b128 v[100:103], v56 offset:41504
	s_waitcnt lgkmcnt(1)
	v_mfma_f32_32x32x16_bf16 v[2:17], v[80:83], v[84:87], v[2:17]
	v_mfma_f32_32x32x16_bf16 v[18:33], v[96:99], v[88:91], v[18:33]
	s_waitcnt lgkmcnt(0)
	v_mfma_f32_32x32x16_bf16 v[2:17], v[96:99], v[100:103], v[2:17]
	ds_read_b128 v[80:83], v0 offset:55360
	ds_read_b128 v[84:87], v56 offset:36928
	ds_read_b128 v[88:91], v56 offset:36960
	ds_read_b128 v[96:99], v0 offset:55392
	s_waitcnt lgkmcnt(2)
	v_mfma_f32_32x32x16_bf16 v[18:33], v[80:83], v[84:87], v[18:33]
	ds_read_b128 v[84:87], v56 offset:41536
	ds_read_b128 v[100:103], v56 offset:41568
	s_waitcnt lgkmcnt(1)
	v_mfma_f32_32x32x16_bf16 v[2:17], v[80:83], v[84:87], v[2:17]
	v_mfma_f32_32x32x16_bf16 v[18:33], v[96:99], v[88:91], v[18:33]
	global_load_dwordx4 v[80:83], v[36:37], off offset:1536
	global_load_dwordx4 v[84:87], v[38:39], off offset:1536
	global_load_dwordx4 v[88:91], v[34:35], off offset:1536
	global_load_dwordx4 v[140:143], v[48:49], off offset:1536
	global_load_dwordx4 v[144:147], v[46:47], off offset:1536
	s_waitcnt vmcnt(12)
	ds_write_b128 v54, v[92:95]
	ds_write_b128 v54, v[60:63] offset:4608
	ds_write_b128 v54, v[64:67] offset:9216
	s_waitcnt vmcnt(10)
	ds_write_b128 v54, v[128:131] offset:13824
	ds_write_b128 v54, v[124:127] offset:18432
	s_waitcnt vmcnt(10)
	s_waitcnt vmcnt(10)
	s_waitcnt vmcnt(10)
	s_waitcnt lgkmcnt(0)
	s_barrier
	v_mfma_f32_32x32x16_bf16 v[2:17], v[96:99], v[100:103], v[2:17]
	ds_read_b128 v[60:63], v0 offset:18432
	ds_read_b128 v[64:67], v56
	ds_read_b128 v[92:95], v56 offset:32
	ds_read_b128 v[96:99], v0 offset:18464
	s_waitcnt lgkmcnt(2)
	v_mfma_f32_32x32x16_bf16 v[18:33], v[60:63], v[64:67], v[18:33]
	ds_read_b128 v[64:67], v56 offset:4608
	ds_read_b128 v[100:103], v56 offset:4640
	s_waitcnt lgkmcnt(1)
	v_mfma_f32_32x32x16_bf16 v[2:17], v[60:63], v[64:67], v[2:17]
	v_mfma_f32_32x32x16_bf16 v[18:33], v[96:99], v[92:95], v[18:33]
	s_waitcnt lgkmcnt(0)
	v_mfma_f32_32x32x16_bf16 v[2:17], v[96:99], v[100:103], v[2:17]
	ds_read_b128 v[60:63], v0 offset:18496
	ds_read_b128 v[64:67], v56 offset:64
	ds_read_b128 v[92:95], v56 offset:96
	ds_read_b128 v[96:99], v0 offset:18528
	s_waitcnt lgkmcnt(2)
	v_mfma_f32_32x32x16_bf16 v[18:33], v[60:63], v[64:67], v[18:33]
	ds_read_b128 v[64:67], v56 offset:4672
	ds_read_b128 v[100:103], v56 offset:4704
	s_waitcnt lgkmcnt(1)
	v_mfma_f32_32x32x16_bf16 v[2:17], v[60:63], v[64:67], v[2:17]
	v_mfma_f32_32x32x16_bf16 v[18:33], v[96:99], v[92:95], v[18:33]
	global_load_dwordx4 v[60:63], v[36:37], off offset:1664
	global_load_dwordx4 v[64:67], v[38:39], off offset:1664
	global_load_dwordx4 v[92:95], v[34:35], off offset:1664
	global_load_dwordx4 v[124:127], v[48:49], off offset:1664
	global_load_dwordx4 v[128:131], v[46:47], off offset:1664
	s_waitcnt vmcnt(12)
	ds_write_b128 v54, v[76:79] offset:36864
	ds_write_b128 v54, v[68:71] offset:41472
	ds_write_b128 v54, v[72:75] offset:46080
	s_waitcnt vmcnt(10)
	ds_write_b128 v54, v[108:111] offset:50688
	ds_write_b128 v54, v[104:107] offset:55296
	s_waitcnt vmcnt(10)
	s_waitcnt vmcnt(10)
	s_waitcnt vmcnt(10)
	s_waitcnt lgkmcnt(0)
	s_barrier
	v_mfma_f32_32x32x16_bf16 v[2:17], v[96:99], v[100:103], v[2:17]
	ds_read_b128 v[68:71], v0 offset:55296
	ds_read_b128 v[72:75], v56 offset:36864
	ds_read_b128 v[76:79], v56 offset:36896
	ds_read_b128 v[96:99], v0 offset:55328
	s_waitcnt lgkmcnt(2)
	v_mfma_f32_32x32x16_bf16 v[18:33], v[68:71], v[72:75], v[18:33]
	ds_read_b128 v[72:75], v56 offset:41472
	ds_read_b128 v[100:103], v56 offset:41504
	s_waitcnt lgkmcnt(1)
	v_mfma_f32_32x32x16_bf16 v[2:17], v[68:71], v[72:75], v[2:17]
	v_mfma_f32_32x32x16_bf16 v[18:33], v[96:99], v[76:79], v[18:33]
	s_waitcnt lgkmcnt(0)
	v_mfma_f32_32x32x16_bf16 v[2:17], v[96:99], v[100:103], v[2:17]
	ds_read_b128 v[68:71], v0 offset:55360
	ds_read_b128 v[72:75], v56 offset:36928
	ds_read_b128 v[76:79], v56 offset:36960
	ds_read_b128 v[96:99], v0 offset:55392
	s_waitcnt lgkmcnt(2)
	v_mfma_f32_32x32x16_bf16 v[18:33], v[68:71], v[72:75], v[18:33]
	ds_read_b128 v[72:75], v56 offset:41536
	ds_read_b128 v[100:103], v56 offset:41568
	s_waitcnt lgkmcnt(1)
	v_mfma_f32_32x32x16_bf16 v[2:17], v[68:71], v[72:75], v[2:17]
	v_mfma_f32_32x32x16_bf16 v[18:33], v[96:99], v[76:79], v[18:33]
	global_load_dwordx4 v[68:71], v[36:37], off offset:1792
	global_load_dwordx4 v[72:75], v[38:39], off offset:1792
	global_load_dwordx4 v[76:79], v[34:35], off offset:1792
	global_load_dwordx4 v[104:107], v[48:49], off offset:1792
	global_load_dwordx4 v[108:111], v[46:47], off offset:1792
	s_waitcnt vmcnt(12)
	ds_write_b128 v54, v[88:91]
	ds_write_b128 v54, v[80:83] offset:4608
	ds_write_b128 v54, v[84:87] offset:9216
	s_waitcnt vmcnt(10)
	ds_write_b128 v54, v[144:147] offset:13824
	ds_write_b128 v54, v[140:143] offset:18432
	s_waitcnt vmcnt(10)
	s_waitcnt vmcnt(10)
	s_waitcnt vmcnt(10)
	s_waitcnt lgkmcnt(0)
	s_barrier
	v_mfma_f32_32x32x16_bf16 v[2:17], v[96:99], v[100:103], v[2:17]
	ds_read_b128 v[80:83], v0 offset:18432
	ds_read_b128 v[84:87], v56
	ds_read_b128 v[88:91], v56 offset:32
	ds_read_b128 v[96:99], v0 offset:18464
	s_waitcnt lgkmcnt(2)
	v_mfma_f32_32x32x16_bf16 v[18:33], v[80:83], v[84:87], v[18:33]
	ds_read_b128 v[84:87], v56 offset:4608
	ds_read_b128 v[100:103], v56 offset:4640
	s_waitcnt lgkmcnt(1)
	v_mfma_f32_32x32x16_bf16 v[2:17], v[80:83], v[84:87], v[2:17]
	v_mfma_f32_32x32x16_bf16 v[18:33], v[96:99], v[88:91], v[18:33]
	s_waitcnt lgkmcnt(0)
	v_mfma_f32_32x32x16_bf16 v[2:17], v[96:99], v[100:103], v[2:17]
	ds_read_b128 v[80:83], v0 offset:18496
	ds_read_b128 v[84:87], v56 offset:64
	ds_read_b128 v[88:91], v56 offset:96
	ds_read_b128 v[96:99], v0 offset:18528
	s_waitcnt lgkmcnt(2)
	v_mfma_f32_32x32x16_bf16 v[18:33], v[80:83], v[84:87], v[18:33]
	ds_read_b128 v[84:87], v56 offset:4672
	ds_read_b128 v[100:103], v56 offset:4704
	s_waitcnt lgkmcnt(1)
	v_mfma_f32_32x32x16_bf16 v[2:17], v[80:83], v[84:87], v[2:17]
	v_mfma_f32_32x32x16_bf16 v[18:33], v[96:99], v[88:91], v[18:33]
	global_load_dwordx4 v[80:83], v[36:37], off offset:1920
	s_nop 0
	global_load_dwordx4 v[36:39], v[38:39], off offset:1920
	s_nop 0
	global_load_dwordx4 v[84:87], v[34:35], off offset:1920
	global_load_dwordx4 v[88:91], v[48:49], off offset:1920
	s_nop 0
	global_load_dwordx4 v[46:49], v[46:47], off offset:1920
	s_nop 0
	s_nop 0
	s_nop 0
	s_waitcnt vmcnt(12)
	ds_write_b128 v54, v[92:95] offset:36864
	ds_write_b128 v54, v[60:63] offset:41472
	ds_write_b128 v54, v[64:67] offset:46080
	s_waitcnt vmcnt(10)
	ds_write_b128 v54, v[128:131] offset:50688
	ds_write_b128 v54, v[124:127] offset:55296
	s_waitcnt vmcnt(10)
	s_waitcnt vmcnt(10)
	s_waitcnt vmcnt(10)
	s_waitcnt lgkmcnt(0)
	s_barrier
	v_mfma_f32_32x32x16_bf16 v[2:17], v[96:99], v[100:103], v[2:17]
	ds_read_b128 v[60:63], v0 offset:55296
	ds_read_b128 v[64:67], v56 offset:36864
	ds_read_b128 v[92:95], v56 offset:36896
	ds_read_b128 v[96:99], v0 offset:55328
	s_waitcnt lgkmcnt(2)
	v_mfma_f32_32x32x16_bf16 v[18:33], v[60:63], v[64:67], v[18:33]
	ds_read_b128 v[64:67], v56 offset:41472
	ds_read_b128 v[100:103], v56 offset:41504
	s_waitcnt lgkmcnt(1)
	v_mfma_f32_32x32x16_bf16 v[2:17], v[60:63], v[64:67], v[2:17]
	v_mfma_f32_32x32x16_bf16 v[18:33], v[96:99], v[92:95], v[18:33]
	s_waitcnt lgkmcnt(0)
	v_mfma_f32_32x32x16_bf16 v[2:17], v[96:99], v[100:103], v[2:17]
	ds_read_b128 v[60:63], v0 offset:55360
	ds_read_b128 v[64:67], v56 offset:36928
	ds_read_b128 v[92:95], v56 offset:36960
	ds_read_b128 v[96:99], v0 offset:55392
	s_waitcnt lgkmcnt(2)
	v_mfma_f32_32x32x16_bf16 v[18:33], v[60:63], v[64:67], v[18:33]
	ds_read_b128 v[64:67], v56 offset:41536
	ds_read_b128 v[100:103], v56 offset:41568
	s_waitcnt vmcnt(7)
	ds_write_b128 v54, v[76:79]
	ds_write_b128 v54, v[68:71] offset:4608
	ds_write_b128 v54, v[72:75] offset:9216
	s_waitcnt vmcnt(5)
	ds_write_b128 v54, v[108:111] offset:13824
	ds_write_b128 v54, v[104:107] offset:18432
	s_waitcnt vmcnt(5)
	s_waitcnt vmcnt(5)
	s_waitcnt vmcnt(5)
	s_waitcnt lgkmcnt(0)
	s_barrier
	v_mfma_f32_32x32x16_bf16 v[2:17], v[60:63], v[64:67], v[2:17]
	ds_read_b128 v[60:63], v0 offset:18432
	ds_read_b128 v[64:67], v56
	ds_read_b128 v[68:71], v56 offset:32
	ds_read_b128 v[72:75], v0 offset:18464
	v_mfma_f32_32x32x16_bf16 v[18:33], v[96:99], v[92:95], v[18:33]
	v_mfma_f32_32x32x16_bf16 v[2:17], v[96:99], v[100:103], v[2:17]
	s_waitcnt lgkmcnt(2)
	v_mfma_f32_32x32x16_bf16 v[18:33], v[60:63], v[64:67], v[18:33]
	ds_read_b128 v[64:67], v56 offset:4608
	ds_read_b128 v[76:79], v56 offset:4640
	s_waitcnt lgkmcnt(1)
	v_mfma_f32_32x32x16_bf16 v[2:17], v[60:63], v[64:67], v[2:17]
	v_mfma_f32_32x32x16_bf16 v[18:33], v[72:75], v[68:71], v[18:33]
	s_waitcnt lgkmcnt(0)
	v_mfma_f32_32x32x16_bf16 v[2:17], v[72:75], v[76:79], v[2:17]
	ds_read_b128 v[60:63], v0 offset:18496
	ds_read_b128 v[64:67], v56 offset:64
	ds_read_b128 v[68:71], v56 offset:96
	ds_read_b128 v[72:75], v0 offset:18528
	s_waitcnt lgkmcnt(2)
	v_mfma_f32_32x32x16_bf16 v[18:33], v[60:63], v[64:67], v[18:33]
	ds_read_b128 v[64:67], v56 offset:4672
	ds_read_b128 v[76:79], v56 offset:4704
	s_waitcnt vmcnt(2)
	ds_write_b128 v54, v[84:87] offset:36864
	ds_write_b128 v54, v[80:83] offset:41472
	ds_write_b128 v54, v[36:39] offset:46080
	s_waitcnt vmcnt(0)
	ds_write_b128 v54, v[46:49] offset:50688
	ds_write_b128 v54, v[88:91] offset:55296
	s_waitcnt vmcnt(0)
	s_waitcnt vmcnt(0)
	s_waitcnt vmcnt(0)
	s_waitcnt lgkmcnt(0)
	s_barrier
	ds_read_b128 v[34:37], v0 offset:55296
	ds_read_b128 v[38:41], v56 offset:36864
	ds_read_b128 v[42:45], v56 offset:36896
	ds_read_b128 v[46:49], v0 offset:55328
	v_mfma_f32_32x32x16_bf16 v[2:17], v[60:63], v[64:67], v[2:17]
	v_mfma_f32_32x32x16_bf16 v[18:33], v[72:75], v[68:71], v[18:33]
	v_mfma_f32_32x32x16_bf16 v[2:17], v[72:75], v[76:79], v[2:17]
	s_waitcnt lgkmcnt(2)
	v_mfma_f32_32x32x16_bf16 v[18:33], v[34:37], v[38:41], v[18:33]
	ds_read_b128 v[38:41], v56 offset:41472
	ds_read_b128 v[58:61], v56 offset:41504
	s_waitcnt lgkmcnt(1)
	v_mfma_f32_32x32x16_bf16 v[2:17], v[34:37], v[38:41], v[2:17]
	v_mfma_f32_32x32x16_bf16 v[18:33], v[46:49], v[42:45], v[18:33]
	s_waitcnt lgkmcnt(0)
	v_mfma_f32_32x32x16_bf16 v[2:17], v[46:49], v[58:61], v[2:17]
	ds_read_b128 v[34:37], v0 offset:55360
	ds_read_b128 v[38:41], v56 offset:36928
	ds_read_b128 v[42:45], v56 offset:36960
	ds_read_b128 v[46:49], v0 offset:55392
	s_waitcnt lgkmcnt(2)
	v_mfma_f32_32x32x16_bf16 v[18:33], v[34:37], v[38:41], v[18:33]
	ds_read_b128 v[38:41], v56 offset:41536
	ds_read_b128 v[56:59], v56 offset:41568
	s_waitcnt lgkmcnt(0)
	s_barrier
	v_mfma_f32_32x32x16_bf16 v[2:17], v[34:37], v[38:41], v[2:17]
	v_mfma_f32_32x32x16_bf16 v[18:33], v[46:49], v[42:45], v[18:33]
	v_add_u32_e32 v42, v51, v55
	v_add_u32_e32 v37, 0x4000, v42
	v_cmp_gt_i32_e32 vcc, s2, v37
	v_cmp_lt_i32_e64 s[38:39], s24, v37
	v_mfma_f32_32x32x16_bf16 v[2:17], v[46:49], v[56:59], v[2:17]
	s_and_saveexec_b64 s[0:1], s[38:39]
	s_xor_b64 s[2:3], exec, s[0:1]
	v_and_b32_e32 v0, 0xdf, v37
	v_lshrrev_b32_e32 v44, 8, v42
	v_or_b32_e32 v0, 0x2000, v0
	s_or_saveexec_b64 s[2:3], s[2:3]
	v_lshrrev_b32_e32 v38, 2, v37
	v_mov_b32_e32 v34, 0
	v_ashrrev_i32_e32 v36, 13, v37
	v_and_b32_e32 v43, 0x7f0, v38
	v_mov_b32_e32 v35, 0
	s_xor_b64 exec, exec, s[2:3]
	v_ashrrev_i32_e32 v44, 13, v37
	v_and_b32_e32 v0, 0x1fdf, v37
	v_and_b32_e32 v34, 0x7f0, v38
	v_lshlrev_b32_e32 v35, 4, v53
	s_or_b64 exec, exec, s[2:3]
	v_bfe_u32 v37, v52, 5, 1
	v_lshlrev_b32_e32 v38, 3, v37
	v_and_b32_e32 v45, 64, v52
	v_or_b32_e32 v39, 2, v38
	v_or_b32_e32 v40, 4, v38
	v_or_b32_e32 v41, 6, v38
	v_lshlrev_b32_e32 v37, 2, v37
	v_cmp_eq_u32_e64 s[38:39], 0, v45
	s_and_saveexec_b64 s[2:3], s[38:39]
	s_cbranch_execz .LBB0_564
	s_and_saveexec_b64 s[22:23], vcc
	s_cbranch_execz .LBB0_563
	v_or_b32_e32 v45, v34, v38
	v_or_b32_e32 v46, v34, v39
	v_or_b32_e32 v52, v34, v40
	v_or_b32_e32 v53, v34, v41
	v_lshlrev_b32_e32 v34, 3, v45
	v_or_b32_e32 v54, v35, v38
	v_or_b32_e32 v55, v35, v39
	v_or_b32_e32 v56, v35, v40
	v_or_b32_e32 v57, v35, v41
	v_lshlrev_b32_e32 v45, 3, v46
	global_load_dwordx2 v[34:35], v34, s[80:81]
	s_nop 0
	global_load_dwordx2 v[46:47], v45, s[80:81]
	v_lshlrev_b32_e32 v45, 3, v53
	s_waitcnt vmcnt(1)
	v_mov_b32_e32 v48, v34
	s_waitcnt vmcnt(0)
	v_mov_b32_e32 v49, v46
	v_mov_b32_e32 v46, v35
	v_mul_f32_e32 v34, v26, v46
	v_mul_f32_e32 v35, v27, v47
	s_nop 0
	v_fma_f32 v34, v18, v48, -v34
	v_fma_f32 v35, v19, v49, -v35
	v_mul_f32_e32 v18, v18, v46
	v_mul_f32_e32 v19, v19, v47
	s_nop 0
	v_fma_f32 v26, v26, v48, v18
	v_fma_f32 v27, v27, v49, v19
	v_lshlrev_b32_e32 v18, 3, v52
	global_load_dwordx2 v[18:19], v18, s[80:81]
	s_nop 0
	global_load_dwordx2 v[46:47], v45, s[80:81]
	s_waitcnt vmcnt(1)
	v_mov_b32_e32 v48, v18
	s_waitcnt vmcnt(0)
	v_mov_b32_e32 v49, v46
	v_mov_b32_e32 v46, v19
	v_mul_f32_e32 v18, v28, v46
	v_mul_f32_e32 v19, v29, v47
	s_nop 0
	v_fma_f32 v52, v20, v48, -v18
	v_fma_f32 v53, v21, v49, -v19
	v_mul_f32_e32 v18, v20, v46
	v_mul_f32_e32 v19, v21, v47
	v_lshlrev_b32_e32 v20, 3, v55
	v_fma_f32 v28, v28, v48, v18
	v_fma_f32 v29, v29, v49, v19
	v_lshlrev_b32_e32 v18, 3, v54
	global_load_dwordx2 v[18:19], v18, s[80:81]
	s_nop 0
	global_load_dwordx2 v[20:21], v20, s[80:81]
	s_waitcnt vmcnt(1)
	v_mov_b32_e32 v46, v18
	s_waitcnt vmcnt(0)
	v_mov_b32_e32 v47, v20
	v_mov_b32_e32 v20, v19
	v_mul_f32_e32 v18, v30, v20
	v_mul_f32_e32 v19, v31, v21
	s_nop 0
	v_fma_f32 v48, v22, v46, -v18
	v_fma_f32 v49, v23, v47, -v19
	v_mul_f32_e32 v18, v22, v20
	v_mul_f32_e32 v19, v23, v21
	v_lshlrev_b32_e32 v20, 3, v56
	v_fma_f32 v30, v30, v46, v18
	v_fma_f32 v31, v31, v47, v19
	v_lshlrev_b32_e32 v18, 3, v57
	global_load_dwordx2 v[18:19], v18, s[80:81]
	s_nop 0
	global_load_dwordx2 v[20:21], v20, s[80:81]
	s_waitcnt vmcnt(1)
	v_mov_b32_e32 v47, v19
	s_waitcnt vmcnt(0)
	v_mov_b32_e32 v46, v21
	v_mov_b32_e32 v22, v20
	v_mov_b32_e32 v23, v18
	v_mul_f32_e32 v46, v32, v46
	v_mul_f32_e32 v47, v33, v47
	v_mul_f32_e32 v20, v32, v20
	v_fma_f32 v46, v24, v22, -v46
	v_fma_f32 v47, v25, v23, -v47
	v_mul_f32_e32 v22, v24, v21
	v_mov_b32_e32 v24, v33
	v_mul_f32_e32 v18, v24, v18
	v_mul_f32_e32 v19, v25, v19
	v_mov_b32_e32 v24, v46
	v_mov_b32_e32 v21, v18
	v_mov_b32_e32 v23, v19
	v_add_f32_e32 v32, v20, v22
	v_add_f32_e32 v33, v21, v23
	v_mov_b32_e32 v18, v34
	v_mov_b32_e32 v19, v35
	v_mov_b32_e32 v20, v52
	v_mov_b32_e32 v21, v53
	v_mov_b32_e32 v22, v48
	v_mov_b32_e32 v23, v49
	v_mov_b32_e32 v25, v47
